# GEMM epilogues: residual (x += acc) tile rows prefetched 3 groups deep with counted vmcnt; in-proj row scales loaded in one burst
# speedup vs baseline: 1.0326x; 1.0025x over previous
; __device__ __forceinline__ unsigned cvt_pk_bf16(float lo, float hi) { unsigned r; asm volatile("v_cvt_pk_bf16_f32 %0, %1, %2" : "=v"(r) : "v"(lo), "v"(hi)); return r; }
;     __device__ __forceinline__ void operator()(const f32x4 (&acc)[2][2][4][2], const Unit& u, int wr, int wc, int fr, int fq) const {
;     ...
;                 const int row = u.pm * BM + ai * HALF + wr * 64 + m * 16 + fr; const size_t off = (size_t)row * D + col0; float part = 0.f;
; #pragma unroll
;                 for (int bj = 0; bj < 2; ++bj)
; #pragma unroll
;                     for (int n = 0; n < 2; ++n) { float* xp = X + off + bj * HALF + n * 16; const f32x4 xv = *(const f32x4*)xp + acc[ai][bj][m][n]; *(f32x4*)xp = xv;
;                         part += (xv[0] * xv[0] + xv[1] * xv[1]) + (xv[2] * xv[2] + xv[3] * xv[3]);
;                         u32x2 w; w.x = cvt_pk_bf16(xv[0], xv[1]); w.y = cvt_pk_bf16(xv[2], xv[3]); *(u32x2*)(XB + off + bj * HALF + n * 16) = w; }
;                 part += __shfl_xor(part, 16); part += __shfl_xor(part, 32);
;                 if (fq == 0) atomicAdd(ssn + row, (u64_t)(part * SS_FX + 0.5f));
.LBB0_93:
	v_lshl_add_u32 v138, s76, 8, v140
	v_lshl_or_b32 v136, s74, 8, v142
	v_ashrrev_i32_e32 v139, 31, v138
	v_ashrrev_i32_e32 v137, 31, v136
	v_lshlrev_b64 v[144:145], 11, v[138:139]
	v_lshl_add_u64 v[148:149], v[144:145], 0, v[136:137]
	v_lshl_add_u64 v[150:151], v[148:149], 2, s[46:47]
	v_mov_b32_e32 v232, v150
	v_mov_b32_e32 v233, v151
	global_load_dwordx4 v[152:155], v[232:233], off
	global_load_dwordx4 v[156:159], v[232:233], off offset:64
	global_load_dwordx4 v[160:163], v[232:233], off offset:512
	global_load_dwordx4 v[164:167], v[232:233], off offset:576
	s_mov_b32 s100, 0x20000
	s_mov_b32 s101, 0
	v_lshl_add_u64 v[230:231], v[232:233], 0, s[100:101]
	global_load_dwordx4 v[168:171], v[230:231], off
	global_load_dwordx4 v[172:175], v[230:231], off offset:64
	global_load_dwordx4 v[186:189], v[230:231], off offset:512
	global_load_dwordx4 v[190:193], v[230:231], off offset:576
	s_mov_b32 s100, 0x40000
	s_mov_b32 s101, 0
	v_lshl_add_u64 v[230:231], v[232:233], 0, s[100:101]
	global_load_dwordx4 v[194:197], v[230:231], off
	global_load_dwordx4 v[198:201], v[230:231], off offset:64
	global_load_dwordx4 v[202:205], v[230:231], off offset:512
	global_load_dwordx4 v[222:225], v[230:231], off offset:576
	s_waitcnt vmcnt(8) lgkmcnt(0)
	s_nop 1
	v_mov_b32_e32 v144, v152
	v_mov_b32_e32 v145, v153
	v_mov_b32_e32 v146, v154
	v_mov_b32_e32 v147, v155
	v_pk_add_f32 v[128:129], v[128:129], v[146:147]
	v_pk_add_f32 v[126:127], v[126:127], v[144:145]
	v_mul_f32_e32 v145, v129, v129
	v_mul_f32_e32 v144, v127, v127
	v_fmac_f32_e32 v144, v126, v126
	v_fmac_f32_e32 v145, v128, v128
	v_add_f32_e32 v146, v144, v145
	v_lshl_add_u64 v[144:145], v[148:149], 1, s[20:21]
	global_store_dwordx4 v[150:151], v[126:129], off
	s_nop 1
	v_cvt_pk_bf16_f32 v126, v126, v127
	v_cvt_pk_bf16_f32 v127, v128, v129
	global_store_dwordx2 v[144:145], v[126:127], off
	s_waitcnt lgkmcnt(0)
	s_nop 1
	v_mov_b32_e32 v126, v156
	v_mov_b32_e32 v127, v157
	v_mov_b32_e32 v128, v158
	v_mov_b32_e32 v129, v159
	v_pk_add_f32 v[122:123], v[122:123], v[126:127]
	v_pk_add_f32 v[124:125], v[124:125], v[128:129]
	v_mul_f32_e32 v126, v123, v123
	global_store_dwordx4 v[150:151], v[122:125], off offset:64
	v_fmac_f32_e32 v126, v122, v122
	v_mul_f32_e32 v127, v125, v125
	v_cvt_pk_bf16_f32 v122, v122, v123
	v_cvt_pk_bf16_f32 v123, v124, v125
	global_store_dwordx2 v[144:145], v[122:123], off offset:32
	v_fmac_f32_e32 v127, v124, v124
	v_add_f32_e32 v126, v126, v127
	v_add_f32_e32 v126, v146, v126
	s_waitcnt lgkmcnt(0)
	s_nop 1
	v_mov_b32_e32 v122, v160
	v_mov_b32_e32 v123, v161
	v_mov_b32_e32 v124, v162
	v_mov_b32_e32 v125, v163
	v_pk_add_f32 v[118:119], v[118:119], v[122:123]
	v_pk_add_f32 v[120:121], v[120:121], v[124:125]
	v_mul_f32_e32 v122, v119, v119
	global_store_dwordx4 v[150:151], v[118:121], off offset:512
	v_fmac_f32_e32 v122, v118, v118
	v_mul_f32_e32 v123, v121, v121
	v_cvt_pk_bf16_f32 v118, v118, v119
	v_cvt_pk_bf16_f32 v119, v120, v121
	global_store_dwordx2 v[144:145], v[118:119], off offset:256
	v_fmac_f32_e32 v123, v120, v120
	v_add_f32_e32 v122, v122, v123
	v_add_f32_e32 v122, v126, v122
	s_waitcnt lgkmcnt(0)
	s_nop 1
	v_mov_b32_e32 v118, v164
	v_mov_b32_e32 v119, v165
	v_mov_b32_e32 v120, v166
	v_mov_b32_e32 v121, v167
	s_mov_b32 s100, 0x60000
	s_mov_b32 s101, 0
	v_lshl_add_u64 v[230:231], v[232:233], 0, s[100:101]
	global_load_dwordx4 v[152:155], v[230:231], off
	global_load_dwordx4 v[156:159], v[230:231], off offset:64
	global_load_dwordx4 v[160:163], v[230:231], off offset:512
	global_load_dwordx4 v[164:167], v[230:231], off offset:576
	v_pk_add_f32 v[114:115], v[114:115], v[118:119]
	v_pk_add_f32 v[116:117], v[116:117], v[120:121]
	v_mul_f32_e32 v118, v115, v115
	global_store_dwordx4 v[150:151], v[114:117], off offset:576
	v_fmac_f32_e32 v118, v114, v114
	v_mul_f32_e32 v119, v117, v117
	v_cvt_pk_bf16_f32 v114, v114, v115
	v_cvt_pk_bf16_f32 v115, v116, v117
	global_store_dwordx2 v[144:145], v[114:115], off offset:288
	v_and_b32_e32 v115, 64, v208
	v_xor_b32_e32 v114, 16, v208
	v_add_u32_e32 v115, 64, v115
	v_fmac_f32_e32 v119, v116, v116
	v_cmp_lt_i32_e32 vcc, v114, v115
	v_add_f32_e32 v118, v118, v119
	v_add_f32_e32 v118, v122, v118
	v_cndmask_b32_e32 v114, v208, v114, vcc
	v_lshlrev_b32_e32 v116, 2, v114
	ds_bpermute_b32 v114, v116, v118
	s_waitcnt lgkmcnt(0)
	v_add_f32_e32 v118, v118, v114
	v_xor_b32_e32 v114, 32, v208
	v_cmp_lt_i32_e32 vcc, v114, v115
	s_nop 1
	v_cndmask_b32_e32 v114, v208, v114, vcc
	v_lshlrev_b32_e32 v117, 2, v114
	ds_bpermute_b32 v119, v117, v118
	v_lshl_add_u64 v[114:115], v[138:139], 3, s[2:3]
	s_and_saveexec_b64 s[12:13], s[38:39]
	s_cbranch_execz .LBB0_95
	s_waitcnt lgkmcnt(0)
	v_add_f32_e32 v118, v118, v119
	s_mov_b32 s14, 0x4b800000
	v_fma_f32 v118, v118, s14, 0.5
	v_trunc_f32_e32 v118, v118
	v_mul_f32_e32 v119, 0x2f800000, v118
	v_floor_f32_e32 v119, v119
	v_fmac_f32_e32 v118, 0xcf800000, v119
	v_cvt_u32_f32_e32 v118, v118
	v_cvt_u32_f32_e32 v119, v119
	global_atomic_add_x2 v[114:115], v[118:119], off
; __device__ __forceinline__ unsigned cvt_pk_bf16(float lo, float hi) { unsigned r; asm volatile("v_cvt_pk_bf16_f32 %0, %1, %2" : "=v"(r) : "v"(lo), "v"(hi)); return r; }
;     __device__ __forceinline__ void operator()(const f32x4 (&acc)[2][2][4][2], const Unit& u, int wr, int wc, int fr, int fq) const {
;     ...
;                 const int row = u.pm * BM + ai * HALF + wr * 64 + m * 16 + fr; const size_t off = (size_t)row * D + col0; float part = 0.f;
; #pragma unroll
;                 for (int bj = 0; bj < 2; ++bj)
; #pragma unroll
;                     for (int n = 0; n < 2; ++n) { float* xp = X + off + bj * HALF + n * 16; const f32x4 xv = *(const f32x4*)xp + acc[ai][bj][m][n]; *(f32x4*)xp = xv;
;                         part += (xv[0] * xv[0] + xv[1] * xv[1]) + (xv[2] * xv[2] + xv[3] * xv[3]);
;                         u32x2 w; w.x = cvt_pk_bf16(xv[0], xv[1]); w.y = cvt_pk_bf16(xv[2], xv[3]); *(u32x2*)(XB + off + bj * HALF + n * 16) = w; }
;                 part += __shfl_xor(part, 16); part += __shfl_xor(part, 32);
;                 if (fq == 0) atomicAdd(ssn + row, (u64_t)(part * SS_FX + 0.5f));
.LBB0_95:
	s_or_b64 exec, exec, s[12:13]
	v_or_b32_e32 v118, 16, v138
	s_waitcnt lgkmcnt(0)
	v_ashrrev_i32_e32 v119, 31, v118
	v_lshlrev_b64 v[118:119], 11, v[118:119]
	v_lshl_add_u64 v[122:123], v[118:119], 0, v[136:137]
	v_lshl_add_u64 v[124:125], v[122:123], 2, s[46:47]
	v_lshl_add_u64 v[122:123], v[122:123], 1, s[20:21]
	s_waitcnt vmcnt(16) lgkmcnt(0)
	s_nop 1
	v_mov_b32_e32 v118, v168
	v_mov_b32_e32 v119, v169
	v_mov_b32_e32 v120, v170
	v_mov_b32_e32 v121, v171
	v_pk_add_f32 v[112:113], v[112:113], v[120:121]
	v_pk_add_f32 v[110:111], v[110:111], v[118:119]
	global_store_dwordx4 v[124:125], v[110:113], off
	v_cvt_pk_bf16_f32 v118, v110, v111
	v_cvt_pk_bf16_f32 v119, v112, v113
	global_store_dwordx2 v[122:123], v[118:119], off
	v_mul_f32_e32 v111, v111, v111
	v_mul_f32_e32 v113, v113, v113
	v_fmac_f32_e32 v111, v110, v110
	v_fmac_f32_e32 v113, v112, v112
	v_add_f32_e32 v110, v111, v113
	s_waitcnt lgkmcnt(0)
	s_nop 1
	v_mov_b32_e32 v118, v172
	v_mov_b32_e32 v119, v173
	v_mov_b32_e32 v120, v174
	v_mov_b32_e32 v121, v175
	v_pk_add_f32 v[108:109], v[108:109], v[120:121]
	v_pk_add_f32 v[106:107], v[106:107], v[118:119]
	global_store_dwordx4 v[124:125], v[106:109], off offset:64
	v_cvt_pk_bf16_f32 v118, v106, v107
	v_cvt_pk_bf16_f32 v119, v108, v109
	global_store_dwordx2 v[122:123], v[118:119], off offset:32
	v_mul_f32_e32 v107, v107, v107
	v_mul_f32_e32 v109, v109, v109
	v_fmac_f32_e32 v107, v106, v106
	v_fmac_f32_e32 v109, v108, v108
	v_add_f32_e32 v106, v107, v109
	v_add_f32_e32 v106, v110, v106
	s_waitcnt lgkmcnt(0)
	s_nop 1
	v_mov_b32_e32 v118, v186
	v_mov_b32_e32 v119, v187
	v_mov_b32_e32 v120, v188
	v_mov_b32_e32 v121, v189
	v_pk_add_f32 v[104:105], v[104:105], v[120:121]
	v_pk_add_f32 v[102:103], v[102:103], v[118:119]
	global_store_dwordx4 v[124:125], v[102:105], off offset:512
	v_cvt_pk_bf16_f32 v118, v102, v103
	v_cvt_pk_bf16_f32 v119, v104, v105
	global_store_dwordx2 v[122:123], v[118:119], off offset:256
	v_mul_f32_e32 v103, v103, v103
	v_mul_f32_e32 v105, v105, v105
	v_fmac_f32_e32 v103, v102, v102
	v_fmac_f32_e32 v105, v104, v104
	v_add_f32_e32 v102, v103, v105
	v_add_f32_e32 v104, v106, v102
	s_waitcnt lgkmcnt(0)
	s_nop 1
	v_mov_b32_e32 v118, v190
	v_mov_b32_e32 v119, v191
	v_mov_b32_e32 v120, v192
	v_mov_b32_e32 v121, v193
	s_mov_b32 s100, 0x100000
	s_mov_b32 s101, 0
	v_lshl_add_u64 v[230:231], v[232:233], 0, s[100:101]
	global_load_dwordx4 v[168:171], v[230:231], off
	global_load_dwordx4 v[172:175], v[230:231], off offset:64
	global_load_dwordx4 v[186:189], v[230:231], off offset:512
	global_load_dwordx4 v[190:193], v[230:231], off offset:576
	v_pk_add_f32 v[102:103], v[100:101], v[120:121]
	v_pk_add_f32 v[100:101], v[98:99], v[118:119]
	v_mul_f32_e32 v99, v103, v103
	v_mul_f32_e32 v98, v101, v101
	v_fmac_f32_e32 v98, v100, v100
	v_fmac_f32_e32 v99, v102, v102
	v_add_f32_e32 v98, v98, v99
	v_add_f32_e32 v98, v104, v98
	ds_bpermute_b32 v99, v116, v98
	global_store_dwordx4 v[124:125], v[100:103], off offset:576
	s_waitcnt lgkmcnt(0)
	v_add_f32_e32 v98, v98, v99
	ds_bpermute_b32 v99, v117, v98
	v_cvt_pk_bf16_f32 v100, v100, v101
	v_cvt_pk_bf16_f32 v101, v102, v103
	global_store_dwordx2 v[122:123], v[100:101], off offset:288
	s_and_saveexec_b64 s[12:13], s[38:39]
	s_cbranch_execz .LBB0_97
	s_waitcnt lgkmcnt(0)
	v_add_f32_e32 v98, v98, v99
	s_mov_b32 s14, 0x4b800000
	v_fma_f32 v98, v98, s14, 0.5
	v_trunc_f32_e32 v98, v98
	v_mul_f32_e32 v99, 0x2f800000, v98
	v_floor_f32_e32 v99, v99
	v_fmac_f32_e32 v98, 0xcf800000, v99
	v_cvt_u32_f32_e32 v98, v98
	v_cvt_u32_f32_e32 v99, v99
	global_atomic_add_x2 v[114:115], v[98:99], off offset:128
.LBB0_97:
	s_or_b64 exec, exec, s[12:13]
	v_or_b32_e32 v98, 32, v138
	s_waitcnt lgkmcnt(0)
	v_ashrrev_i32_e32 v99, 31, v98
	v_lshlrev_b64 v[98:99], 11, v[98:99]
	v_lshl_add_u64 v[102:103], v[98:99], 0, v[136:137]
	v_lshl_add_u64 v[104:105], v[102:103], 2, s[46:47]
	v_lshl_add_u64 v[102:103], v[102:103], 1, s[20:21]
	s_waitcnt vmcnt(24) lgkmcnt(0)
	s_nop 1
	v_mov_b32_e32 v98, v194
	v_mov_b32_e32 v99, v195
	v_mov_b32_e32 v100, v196
	v_mov_b32_e32 v101, v197
	v_pk_add_f32 v[96:97], v[96:97], v[100:101]
	v_pk_add_f32 v[94:95], v[94:95], v[98:99]
	global_store_dwordx4 v[104:105], v[94:97], off
	v_cvt_pk_bf16_f32 v98, v94, v95
	v_cvt_pk_bf16_f32 v99, v96, v97
	global_store_dwordx2 v[102:103], v[98:99], off
	v_mul_f32_e32 v95, v95, v95
	v_mul_f32_e32 v97, v97, v97
	v_fmac_f32_e32 v95, v94, v94
	v_fmac_f32_e32 v97, v96, v96
	v_add_f32_e32 v94, v95, v97
	s_waitcnt lgkmcnt(0)
	s_nop 1
	v_mov_b32_e32 v98, v198
	v_mov_b32_e32 v99, v199
	v_mov_b32_e32 v100, v200
	v_mov_b32_e32 v101, v201
	v_pk_add_f32 v[92:93], v[92:93], v[100:101]
	v_pk_add_f32 v[90:91], v[90:91], v[98:99]
	global_store_dwordx4 v[104:105], v[90:93], off offset:64
	v_cvt_pk_bf16_f32 v98, v90, v91
	v_cvt_pk_bf16_f32 v99, v92, v93
	global_store_dwordx2 v[102:103], v[98:99], off offset:32
	v_mul_f32_e32 v91, v91, v91
	v_mul_f32_e32 v93, v93, v93
	v_fmac_f32_e32 v91, v90, v90
	v_fmac_f32_e32 v93, v92, v92
	v_add_f32_e32 v90, v91, v93
	v_add_f32_e32 v90, v94, v90
	s_waitcnt lgkmcnt(0)
	s_nop 1
	v_mov_b32_e32 v98, v202
	v_mov_b32_e32 v99, v203
	v_mov_b32_e32 v100, v204
	v_mov_b32_e32 v101, v205
	v_pk_add_f32 v[88:89], v[88:89], v[100:101]
	v_pk_add_f32 v[86:87], v[86:87], v[98:99]
	global_store_dwordx4 v[104:105], v[86:89], off offset:512
	v_cvt_pk_bf16_f32 v98, v86, v87
	v_cvt_pk_bf16_f32 v99, v88, v89
	global_store_dwordx2 v[102:103], v[98:99], off offset:256
	v_mul_f32_e32 v87, v87, v87
	v_mul_f32_e32 v89, v89, v89
	v_fmac_f32_e32 v87, v86, v86
	v_fmac_f32_e32 v89, v88, v88
	v_add_f32_e32 v86, v87, v89
	v_add_f32_e32 v88, v90, v86
	s_waitcnt lgkmcnt(0)
	s_nop 1
	v_mov_b32_e32 v98, v222
	v_mov_b32_e32 v99, v223
	v_mov_b32_e32 v100, v224
	v_mov_b32_e32 v101, v225
	s_mov_b32 s100, 0x120000
	s_mov_b32 s101, 0
	v_lshl_add_u64 v[230:231], v[232:233], 0, s[100:101]
	global_load_dwordx4 v[194:197], v[230:231], off
	global_load_dwordx4 v[198:201], v[230:231], off offset:64
	global_load_dwordx4 v[202:205], v[230:231], off offset:512
	global_load_dwordx4 v[222:225], v[230:231], off offset:576
	v_pk_add_f32 v[86:87], v[84:85], v[100:101]
	v_pk_add_f32 v[84:85], v[82:83], v[98:99]
	v_mul_f32_e32 v83, v87, v87
	v_mul_f32_e32 v82, v85, v85
	v_fmac_f32_e32 v82, v84, v84
	v_fmac_f32_e32 v83, v86, v86
	v_add_f32_e32 v82, v82, v83
	v_add_f32_e32 v82, v88, v82
	ds_bpermute_b32 v83, v116, v82
	global_store_dwordx4 v[104:105], v[84:87], off offset:576
	s_waitcnt lgkmcnt(0)
	v_add_f32_e32 v82, v82, v83
	ds_bpermute_b32 v83, v117, v82
	v_cvt_pk_bf16_f32 v84, v84, v85
	v_cvt_pk_bf16_f32 v85, v86, v87
	global_store_dwordx2 v[102:103], v[84:85], off offset:288
	s_and_saveexec_b64 s[12:13], s[38:39]
	s_movk_i32 s75, 0x1fff
	s_mov_b32 s77, 0x6300000
	s_movk_i32 s81, 0x90
	s_cbranch_execz .LBB0_99
; __device__ __forceinline__ unsigned cvt_pk_bf16(float lo, float hi) { unsigned r; asm volatile("v_cvt_pk_bf16_f32 %0, %1, %2" : "=v"(r) : "v"(lo), "v"(hi)); return r; }
;     __device__ __forceinline__ void operator()(const f32x4 (&acc)[2][2][4][2], const Unit& u, int wr, int wc, int fr, int fq) const {
;     ...
;                 const int row = u.pm * BM + ai * HALF + wr * 64 + m * 16 + fr; const size_t off = (size_t)row * D + col0; float part = 0.f;
; #pragma unroll
;                 for (int bj = 0; bj < 2; ++bj)
; #pragma unroll
;                     for (int n = 0; n < 2; ++n) { float* xp = X + off + bj * HALF + n * 16; const f32x4 xv = *(const f32x4*)xp + acc[ai][bj][m][n]; *(f32x4*)xp = xv;
;                         part += (xv[0] * xv[0] + xv[1] * xv[1]) + (xv[2] * xv[2] + xv[3] * xv[3]);
;                         u32x2 w; w.x = cvt_pk_bf16(xv[0], xv[1]); w.y = cvt_pk_bf16(xv[2], xv[3]); *(u32x2*)(XB + off + bj * HALF + n * 16) = w; }
;                 part += __shfl_xor(part, 16); part += __shfl_xor(part, 32);
;                 if (fq == 0) atomicAdd(ssn + row, (u64_t)(part * SS_FX + 0.5f));
	s_waitcnt lgkmcnt(0)
	v_add_f32_e32 v82, v82, v83
	s_mov_b32 s14, 0x4b800000
	v_fma_f32 v82, v82, s14, 0.5
	v_trunc_f32_e32 v82, v82
	v_mul_f32_e32 v83, 0x2f800000, v82
	v_floor_f32_e32 v83, v83
	v_fmac_f32_e32 v82, 0xcf800000, v83
	v_cvt_u32_f32_e32 v82, v82
	v_cvt_u32_f32_e32 v83, v83
	global_atomic_add_x2 v[114:115], v[82:83], off offset:256
.LBB0_99:
	s_or_b64 exec, exec, s[12:13]
	v_or_b32_e32 v82, 48, v138
	s_waitcnt lgkmcnt(0)
	v_ashrrev_i32_e32 v83, 31, v82
	v_lshlrev_b64 v[82:83], 11, v[82:83]
	v_lshl_add_u64 v[86:87], v[82:83], 0, v[136:137]
	v_lshl_add_u64 v[88:89], v[86:87], 2, s[46:47]
	v_lshl_add_u64 v[86:87], v[86:87], 1, s[20:21]
	s_waitcnt vmcnt(26) lgkmcnt(0)
	s_nop 1
	v_mov_b32_e32 v82, v152
	v_mov_b32_e32 v83, v153
	v_mov_b32_e32 v84, v154
	v_mov_b32_e32 v85, v155
	v_pk_add_f32 v[80:81], v[80:81], v[84:85]
	v_pk_add_f32 v[78:79], v[78:79], v[82:83]
	global_store_dwordx4 v[88:89], v[78:81], off
	v_cvt_pk_bf16_f32 v82, v78, v79
	v_cvt_pk_bf16_f32 v83, v80, v81
	global_store_dwordx2 v[86:87], v[82:83], off
	v_mul_f32_e32 v79, v79, v79
	v_mul_f32_e32 v81, v81, v81
	v_fmac_f32_e32 v79, v78, v78
	v_fmac_f32_e32 v81, v80, v80
	v_add_f32_e32 v78, v79, v81
	s_waitcnt lgkmcnt(0)
	s_nop 1
	v_mov_b32_e32 v82, v156
	v_mov_b32_e32 v83, v157
	v_mov_b32_e32 v84, v158
	v_mov_b32_e32 v85, v159
	v_pk_add_f32 v[76:77], v[76:77], v[84:85]
	v_pk_add_f32 v[74:75], v[74:75], v[82:83]
	global_store_dwordx4 v[88:89], v[74:77], off offset:64
	v_cvt_pk_bf16_f32 v82, v74, v75
	v_cvt_pk_bf16_f32 v83, v76, v77
	global_store_dwordx2 v[86:87], v[82:83], off offset:32
	v_mul_f32_e32 v75, v75, v75
	v_mul_f32_e32 v77, v77, v77
	v_fmac_f32_e32 v75, v74, v74
	v_fmac_f32_e32 v77, v76, v76
	v_add_f32_e32 v74, v75, v77
	v_add_f32_e32 v74, v78, v74
	s_waitcnt lgkmcnt(0)
	s_nop 1
	v_mov_b32_e32 v82, v160
	v_mov_b32_e32 v83, v161
	v_mov_b32_e32 v84, v162
	v_mov_b32_e32 v85, v163
	v_pk_add_f32 v[72:73], v[72:73], v[84:85]
	v_pk_add_f32 v[70:71], v[70:71], v[82:83]
	global_store_dwordx4 v[88:89], v[70:73], off offset:512
	v_cvt_pk_bf16_f32 v82, v70, v71
	v_cvt_pk_bf16_f32 v83, v72, v73
	global_store_dwordx2 v[86:87], v[82:83], off offset:256
	v_mul_f32_e32 v71, v71, v71
	v_mul_f32_e32 v73, v73, v73
	v_fmac_f32_e32 v71, v70, v70
	v_fmac_f32_e32 v73, v72, v72
	v_add_f32_e32 v70, v71, v73
	v_add_f32_e32 v72, v74, v70
	s_waitcnt lgkmcnt(0)
	s_nop 1
	v_mov_b32_e32 v82, v164
	v_mov_b32_e32 v83, v165
	v_mov_b32_e32 v84, v166
	v_mov_b32_e32 v85, v167
	s_mov_b32 s100, 0x140000
	s_mov_b32 s101, 0
	v_lshl_add_u64 v[230:231], v[232:233], 0, s[100:101]
	global_load_dwordx4 v[152:155], v[230:231], off
	global_load_dwordx4 v[156:159], v[230:231], off offset:64
	global_load_dwordx4 v[160:163], v[230:231], off offset:512
	global_load_dwordx4 v[164:167], v[230:231], off offset:576
	v_pk_add_f32 v[70:71], v[68:69], v[84:85]
	v_pk_add_f32 v[68:69], v[66:67], v[82:83]
	v_mul_f32_e32 v67, v71, v71
	v_mul_f32_e32 v66, v69, v69
	v_fmac_f32_e32 v66, v68, v68
	v_fmac_f32_e32 v67, v70, v70
	v_add_f32_e32 v66, v66, v67
	v_add_f32_e32 v66, v72, v66
	ds_bpermute_b32 v67, v116, v66
	global_store_dwordx4 v[88:89], v[68:71], off offset:576
	s_waitcnt lgkmcnt(0)
	v_add_f32_e32 v66, v66, v67
	ds_bpermute_b32 v67, v117, v66
	v_cvt_pk_bf16_f32 v68, v68, v69
	v_cvt_pk_bf16_f32 v69, v70, v71
	global_store_dwordx2 v[86:87], v[68:69], off offset:288
	s_and_saveexec_b64 s[12:13], s[38:39]
	s_cbranch_execz .LBB0_101
	s_waitcnt lgkmcnt(0)
	v_add_f32_e32 v66, v66, v67
	s_mov_b32 s14, 0x4b800000
	v_fma_f32 v66, v66, s14, 0.5
	v_trunc_f32_e32 v66, v66
	v_mul_f32_e32 v67, 0x2f800000, v66
	v_floor_f32_e32 v67, v67
	v_fmac_f32_e32 v66, 0xcf800000, v67
	v_cvt_u32_f32_e32 v66, v66
	v_cvt_u32_f32_e32 v67, v67
	global_atomic_add_x2 v[114:115], v[66:67], off offset:384
.LBB0_101:
	s_or_b64 exec, exec, s[12:13]
	v_add_u32_e32 v66, 0x80, v138
	s_waitcnt lgkmcnt(0)
	v_ashrrev_i32_e32 v67, 31, v66
	v_lshlrev_b64 v[66:67], 11, v[66:67]
	v_lshl_add_u64 v[70:71], v[66:67], 0, v[136:137]
	v_lshl_add_u64 v[72:73], v[70:71], 2, s[46:47]
	v_lshl_add_u64 v[70:71], v[70:71], 1, s[20:21]
	s_waitcnt vmcnt(26) lgkmcnt(0)
	s_nop 1
	v_mov_b32_e32 v66, v168
	v_mov_b32_e32 v67, v169
	v_mov_b32_e32 v68, v170
	v_mov_b32_e32 v69, v171
	v_pk_add_f32 v[64:65], v[64:65], v[68:69]
	v_pk_add_f32 v[62:63], v[62:63], v[66:67]
	global_store_dwordx4 v[72:73], v[62:65], off
	v_cvt_pk_bf16_f32 v66, v62, v63
	v_cvt_pk_bf16_f32 v67, v64, v65
	global_store_dwordx2 v[70:71], v[66:67], off
	v_mul_f32_e32 v63, v63, v63
	v_mul_f32_e32 v65, v65, v65
	v_fmac_f32_e32 v63, v62, v62
	v_fmac_f32_e32 v65, v64, v64
	v_add_f32_e32 v62, v63, v65
	s_waitcnt lgkmcnt(0)
	s_nop 1
	v_mov_b32_e32 v66, v172
	v_mov_b32_e32 v67, v173
	v_mov_b32_e32 v68, v174
	v_mov_b32_e32 v69, v175
	v_pk_add_f32 v[60:61], v[60:61], v[68:69]
	v_pk_add_f32 v[58:59], v[58:59], v[66:67]
	global_store_dwordx4 v[72:73], v[58:61], off offset:64
	v_cvt_pk_bf16_f32 v66, v58, v59
	v_cvt_pk_bf16_f32 v67, v60, v61
	global_store_dwordx2 v[70:71], v[66:67], off offset:32
	v_mul_f32_e32 v59, v59, v59
	v_mul_f32_e32 v61, v61, v61
	v_fmac_f32_e32 v59, v58, v58
	v_fmac_f32_e32 v61, v60, v60
	v_add_f32_e32 v58, v59, v61
	v_add_f32_e32 v58, v62, v58
	s_waitcnt lgkmcnt(0)
	s_nop 1
	v_mov_b32_e32 v66, v186
	v_mov_b32_e32 v67, v187
	v_mov_b32_e32 v68, v188
	v_mov_b32_e32 v69, v189
	v_pk_add_f32 v[56:57], v[56:57], v[68:69]
	v_pk_add_f32 v[54:55], v[54:55], v[66:67]
	global_store_dwordx4 v[72:73], v[54:57], off offset:512
	v_cvt_pk_bf16_f32 v66, v54, v55
	v_cvt_pk_bf16_f32 v67, v56, v57
	global_store_dwordx2 v[70:71], v[66:67], off offset:256
	v_mul_f32_e32 v55, v55, v55
	v_mul_f32_e32 v57, v57, v57
	v_fmac_f32_e32 v55, v54, v54
	v_fmac_f32_e32 v57, v56, v56
	v_add_f32_e32 v54, v55, v57
	v_add_f32_e32 v56, v58, v54
	s_waitcnt lgkmcnt(0)
	s_nop 1
	v_mov_b32_e32 v66, v190
	v_mov_b32_e32 v67, v191
	v_mov_b32_e32 v68, v192
	v_mov_b32_e32 v69, v193
	s_mov_b32 s100, 0x160000
	s_mov_b32 s101, 0
	v_lshl_add_u64 v[230:231], v[232:233], 0, s[100:101]
	global_load_dwordx4 v[168:171], v[230:231], off
	global_load_dwordx4 v[172:175], v[230:231], off offset:64
	global_load_dwordx4 v[186:189], v[230:231], off offset:512
	global_load_dwordx4 v[190:193], v[230:231], off offset:576
	v_pk_add_f32 v[54:55], v[52:53], v[68:69]
	v_pk_add_f32 v[52:53], v[50:51], v[66:67]
	v_mul_f32_e32 v51, v55, v55
	v_mul_f32_e32 v50, v53, v53
	v_fmac_f32_e32 v50, v52, v52
	v_fmac_f32_e32 v51, v54, v54
	v_add_f32_e32 v50, v50, v51
	v_add_f32_e32 v50, v56, v50
	ds_bpermute_b32 v51, v116, v50
	global_store_dwordx4 v[72:73], v[52:55], off offset:576
	s_waitcnt lgkmcnt(0)
	v_add_f32_e32 v50, v50, v51
	ds_bpermute_b32 v51, v117, v50
	v_cvt_pk_bf16_f32 v52, v52, v53
	v_cvt_pk_bf16_f32 v53, v54, v55
	global_store_dwordx2 v[70:71], v[52:53], off offset:288
	s_and_saveexec_b64 s[12:13], s[38:39]
	s_cbranch_execz .LBB0_103
; __device__ __forceinline__ unsigned cvt_pk_bf16(float lo, float hi) { unsigned r; asm volatile("v_cvt_pk_bf16_f32 %0, %1, %2" : "=v"(r) : "v"(lo), "v"(hi)); return r; }
;     __device__ __forceinline__ void operator()(const f32x4 (&acc)[2][2][4][2], const Unit& u, int wr, int wc, int fr, int fq) const {
;     ...
;                 const int row = u.pm * BM + ai * HALF + wr * 64 + m * 16 + fr; const size_t off = (size_t)row * D + col0; float part = 0.f;
; #pragma unroll
;                 for (int bj = 0; bj < 2; ++bj)
; #pragma unroll
;                     for (int n = 0; n < 2; ++n) { float* xp = X + off + bj * HALF + n * 16; const f32x4 xv = *(const f32x4*)xp + acc[ai][bj][m][n]; *(f32x4*)xp = xv;
;                         part += (xv[0] * xv[0] + xv[1] * xv[1]) + (xv[2] * xv[2] + xv[3] * xv[3]);
;                         u32x2 w; w.x = cvt_pk_bf16(xv[0], xv[1]); w.y = cvt_pk_bf16(xv[2], xv[3]); *(u32x2*)(XB + off + bj * HALF + n * 16) = w; }
;                 part += __shfl_xor(part, 16); part += __shfl_xor(part, 32);
;                 if (fq == 0) atomicAdd(ssn + row, (u64_t)(part * SS_FX + 0.5f));
	s_waitcnt lgkmcnt(0)
	v_add_f32_e32 v50, v50, v51
	s_mov_b32 s14, 0x4b800000
	v_fma_f32 v50, v50, s14, 0.5
	v_trunc_f32_e32 v50, v50
	v_mul_f32_e32 v51, 0x2f800000, v50
	v_floor_f32_e32 v51, v51
	v_fmac_f32_e32 v50, 0xcf800000, v51
	v_cvt_u32_f32_e32 v50, v50
	v_cvt_u32_f32_e32 v51, v51
	global_atomic_add_x2 v[114:115], v[50:51], off offset:1024
.LBB0_103:
	s_or_b64 exec, exec, s[12:13]
	v_add_u32_e32 v50, 0x90, v138
	s_waitcnt lgkmcnt(0)
	v_ashrrev_i32_e32 v51, 31, v50
	v_lshlrev_b64 v[50:51], 11, v[50:51]
	v_lshl_add_u64 v[54:55], v[50:51], 0, v[136:137]
	v_lshl_add_u64 v[56:57], v[54:55], 2, s[46:47]
	v_lshl_add_u64 v[54:55], v[54:55], 1, s[20:21]
	s_waitcnt vmcnt(26) lgkmcnt(0)
	s_nop 1
	v_mov_b32_e32 v50, v194
	v_mov_b32_e32 v51, v195
	v_mov_b32_e32 v52, v196
	v_mov_b32_e32 v53, v197
	v_pk_add_f32 v[48:49], v[48:49], v[52:53]
	v_pk_add_f32 v[46:47], v[46:47], v[50:51]
	global_store_dwordx4 v[56:57], v[46:49], off
	v_cvt_pk_bf16_f32 v50, v46, v47
	v_cvt_pk_bf16_f32 v51, v48, v49
	global_store_dwordx2 v[54:55], v[50:51], off
	v_mul_f32_e32 v47, v47, v47
	v_mul_f32_e32 v49, v49, v49
	v_fmac_f32_e32 v47, v46, v46
	v_fmac_f32_e32 v49, v48, v48
	v_add_f32_e32 v46, v47, v49
	s_waitcnt lgkmcnt(0)
	s_nop 1
	v_mov_b32_e32 v50, v198
	v_mov_b32_e32 v51, v199
	v_mov_b32_e32 v52, v200
	v_mov_b32_e32 v53, v201
	v_pk_add_f32 v[44:45], v[44:45], v[52:53]
	v_pk_add_f32 v[42:43], v[42:43], v[50:51]
	global_store_dwordx4 v[56:57], v[42:45], off offset:64
	v_cvt_pk_bf16_f32 v50, v42, v43
	v_cvt_pk_bf16_f32 v51, v44, v45
	global_store_dwordx2 v[54:55], v[50:51], off offset:32
	v_mul_f32_e32 v43, v43, v43
	v_mul_f32_e32 v45, v45, v45
	v_fmac_f32_e32 v43, v42, v42
	v_fmac_f32_e32 v45, v44, v44
	v_add_f32_e32 v42, v43, v45
	v_add_f32_e32 v42, v46, v42
	s_waitcnt lgkmcnt(0)
	s_nop 1
	v_mov_b32_e32 v50, v202
	v_mov_b32_e32 v51, v203
	v_mov_b32_e32 v52, v204
	v_mov_b32_e32 v53, v205
	v_pk_add_f32 v[40:41], v[40:41], v[52:53]
	v_pk_add_f32 v[38:39], v[38:39], v[50:51]
	global_store_dwordx4 v[56:57], v[38:41], off offset:512
	v_cvt_pk_bf16_f32 v50, v38, v39
	v_cvt_pk_bf16_f32 v51, v40, v41
	global_store_dwordx2 v[54:55], v[50:51], off offset:256
	v_mul_f32_e32 v39, v39, v39
	v_mul_f32_e32 v41, v41, v41
	v_fmac_f32_e32 v39, v38, v38
	v_fmac_f32_e32 v41, v40, v40
	v_add_f32_e32 v38, v39, v41
	v_add_f32_e32 v40, v42, v38
	s_waitcnt lgkmcnt(0)
	s_nop 1
	v_mov_b32_e32 v50, v222
	v_mov_b32_e32 v51, v223
	v_mov_b32_e32 v52, v224
	v_mov_b32_e32 v53, v225
	v_pk_add_f32 v[38:39], v[36:37], v[52:53]
	v_pk_add_f32 v[36:37], v[34:35], v[50:51]
	v_mul_f32_e32 v35, v39, v39
	v_mul_f32_e32 v34, v37, v37
	v_fmac_f32_e32 v34, v36, v36
	v_fmac_f32_e32 v35, v38, v38
	v_add_f32_e32 v34, v34, v35
	v_add_f32_e32 v34, v40, v34
	ds_bpermute_b32 v35, v116, v34
	global_store_dwordx4 v[56:57], v[36:39], off offset:576
	s_waitcnt lgkmcnt(0)
	v_add_f32_e32 v34, v34, v35
	ds_bpermute_b32 v35, v117, v34
	v_cvt_pk_bf16_f32 v36, v36, v37
	v_cvt_pk_bf16_f32 v37, v38, v39
	global_store_dwordx2 v[54:55], v[36:37], off offset:288
	s_and_saveexec_b64 s[12:13], s[38:39]
	s_cbranch_execz .LBB0_105
	s_waitcnt lgkmcnt(0)
	v_add_f32_e32 v34, v34, v35
	s_mov_b32 s14, 0x4b800000
	v_fma_f32 v34, v34, s14, 0.5
	v_trunc_f32_e32 v34, v34
	v_mul_f32_e32 v35, 0x2f800000, v34
	v_floor_f32_e32 v35, v35
	v_fmac_f32_e32 v34, 0xcf800000, v35
	v_cvt_u32_f32_e32 v34, v34
	v_cvt_u32_f32_e32 v35, v35
	global_atomic_add_x2 v[114:115], v[34:35], off offset:1152
; __device__ __forceinline__ unsigned cvt_pk_bf16(float lo, float hi) { unsigned r; asm volatile("v_cvt_pk_bf16_f32 %0, %1, %2" : "=v"(r) : "v"(lo), "v"(hi)); return r; }
;     __device__ __forceinline__ void operator()(const f32x4 (&acc)[2][2][4][2], const Unit& u, int wr, int wc, int fr, int fq) const {
;     ...
;                 const int row = u.pm * BM + ai * HALF + wr * 64 + m * 16 + fr; const size_t off = (size_t)row * D + col0; float part = 0.f;
; #pragma unroll
;                 for (int bj = 0; bj < 2; ++bj)
; #pragma unroll
;                     for (int n = 0; n < 2; ++n) { float* xp = X + off + bj * HALF + n * 16; const f32x4 xv = *(const f32x4*)xp + acc[ai][bj][m][n]; *(f32x4*)xp = xv;
;                         part += (xv[0] * xv[0] + xv[1] * xv[1]) + (xv[2] * xv[2] + xv[3] * xv[3]);
;                         u32x2 w; w.x = cvt_pk_bf16(xv[0], xv[1]); w.y = cvt_pk_bf16(xv[2], xv[3]); *(u32x2*)(XB + off + bj * HALF + n * 16) = w; }
;                 part += __shfl_xor(part, 16); part += __shfl_xor(part, 32);
;                 if (fq == 0) atomicAdd(ssn + row, (u64_t)(part * SS_FX + 0.5f));
.LBB0_105:
	s_or_b64 exec, exec, s[12:13]
	v_add_u32_e32 v34, 0xa0, v138
	s_waitcnt lgkmcnt(0)
	v_ashrrev_i32_e32 v35, 31, v34
	v_lshlrev_b64 v[34:35], 11, v[34:35]
	v_lshl_add_u64 v[38:39], v[34:35], 0, v[136:137]
	v_lshl_add_u64 v[40:41], v[38:39], 2, s[46:47]
	v_lshl_add_u64 v[38:39], v[38:39], 1, s[20:21]
	s_waitcnt vmcnt(22) lgkmcnt(0)
	s_nop 1
	v_mov_b32_e32 v34, v152
	v_mov_b32_e32 v35, v153
	v_mov_b32_e32 v36, v154
	v_mov_b32_e32 v37, v155
	v_pk_add_f32 v[32:33], v[32:33], v[36:37]
	v_pk_add_f32 v[30:31], v[30:31], v[34:35]
	global_store_dwordx4 v[40:41], v[30:33], off
	v_cvt_pk_bf16_f32 v34, v30, v31
	v_cvt_pk_bf16_f32 v35, v32, v33
	global_store_dwordx2 v[38:39], v[34:35], off
	v_mul_f32_e32 v31, v31, v31
	v_mul_f32_e32 v33, v33, v33
	v_fmac_f32_e32 v31, v30, v30
	v_fmac_f32_e32 v33, v32, v32
	v_add_f32_e32 v30, v31, v33
	s_waitcnt lgkmcnt(0)
	s_nop 1
	v_mov_b32_e32 v34, v156
	v_mov_b32_e32 v35, v157
	v_mov_b32_e32 v36, v158
	v_mov_b32_e32 v37, v159
	v_pk_add_f32 v[28:29], v[28:29], v[36:37]
	v_pk_add_f32 v[26:27], v[26:27], v[34:35]
	global_store_dwordx4 v[40:41], v[26:29], off offset:64
	v_cvt_pk_bf16_f32 v34, v26, v27
	v_cvt_pk_bf16_f32 v35, v28, v29
	global_store_dwordx2 v[38:39], v[34:35], off offset:32
	v_mul_f32_e32 v27, v27, v27
	v_mul_f32_e32 v29, v29, v29
	v_fmac_f32_e32 v27, v26, v26
	v_fmac_f32_e32 v29, v28, v28
	v_add_f32_e32 v26, v27, v29
	v_add_f32_e32 v26, v30, v26
	s_waitcnt lgkmcnt(0)
	s_nop 1
	v_mov_b32_e32 v34, v160
	v_mov_b32_e32 v35, v161
	v_mov_b32_e32 v36, v162
	v_mov_b32_e32 v37, v163
	v_pk_add_f32 v[24:25], v[24:25], v[36:37]
	v_pk_add_f32 v[22:23], v[22:23], v[34:35]
	global_store_dwordx4 v[40:41], v[22:25], off offset:512
	v_cvt_pk_bf16_f32 v34, v22, v23
	v_cvt_pk_bf16_f32 v35, v24, v25
	global_store_dwordx2 v[38:39], v[34:35], off offset:256
	v_mul_f32_e32 v23, v23, v23
	v_mul_f32_e32 v25, v25, v25
	v_fmac_f32_e32 v23, v22, v22
	v_fmac_f32_e32 v25, v24, v24
	v_add_f32_e32 v22, v23, v25
	v_add_f32_e32 v24, v26, v22
	s_waitcnt lgkmcnt(0)
	s_nop 1
	v_mov_b32_e32 v34, v164
	v_mov_b32_e32 v35, v165
	v_mov_b32_e32 v36, v166
	v_mov_b32_e32 v37, v167
	v_pk_add_f32 v[22:23], v[20:21], v[36:37]
	v_pk_add_f32 v[20:21], v[18:19], v[34:35]
	v_mul_f32_e32 v19, v23, v23
	v_mul_f32_e32 v18, v21, v21
	v_fmac_f32_e32 v18, v20, v20
	v_fmac_f32_e32 v19, v22, v22
	v_add_f32_e32 v18, v18, v19
	v_add_f32_e32 v18, v24, v18
	ds_bpermute_b32 v19, v116, v18
	global_store_dwordx4 v[40:41], v[20:23], off offset:576
	s_waitcnt lgkmcnt(0)
	v_add_f32_e32 v18, v18, v19
	ds_bpermute_b32 v19, v117, v18
	v_cvt_pk_bf16_f32 v20, v20, v21
	v_cvt_pk_bf16_f32 v21, v22, v23
	global_store_dwordx2 v[38:39], v[20:21], off offset:288
	s_and_saveexec_b64 s[12:13], s[38:39]
	s_cbranch_execz .LBB0_107
	s_waitcnt lgkmcnt(0)
	v_add_f32_e32 v18, v18, v19
	s_mov_b32 s14, 0x4b800000
	v_fma_f32 v18, v18, s14, 0.5
	v_trunc_f32_e32 v18, v18
	v_mul_f32_e32 v19, 0x2f800000, v18
	v_floor_f32_e32 v19, v19
	v_fmac_f32_e32 v18, 0xcf800000, v19
	v_cvt_u32_f32_e32 v18, v18
	v_cvt_u32_f32_e32 v19, v19
	global_atomic_add_x2 v[114:115], v[18:19], off offset:1280
.LBB0_107:
	s_or_b64 exec, exec, s[12:13]
	v_add_u32_e32 v18, 0xb0, v138
	s_waitcnt lgkmcnt(0)
	v_ashrrev_i32_e32 v19, 31, v18
	v_lshlrev_b64 v[18:19], 11, v[18:19]
	v_lshl_add_u64 v[22:23], v[18:19], 0, v[136:137]
	v_lshl_add_u64 v[24:25], v[22:23], 2, s[46:47]
	v_lshl_add_u64 v[22:23], v[22:23], 1, s[20:21]
	s_waitcnt vmcnt(18) lgkmcnt(0)
	s_nop 1
	v_mov_b32_e32 v18, v168
	v_mov_b32_e32 v19, v169
	v_mov_b32_e32 v20, v170
	v_mov_b32_e32 v21, v171
	v_pk_add_f32 v[16:17], v[16:17], v[20:21]
	v_pk_add_f32 v[14:15], v[14:15], v[18:19]
	global_store_dwordx4 v[24:25], v[14:17], off
	v_cvt_pk_bf16_f32 v18, v14, v15
	v_cvt_pk_bf16_f32 v19, v16, v17
	global_store_dwordx2 v[22:23], v[18:19], off
	v_mul_f32_e32 v15, v15, v15
	v_mul_f32_e32 v17, v17, v17
	v_fmac_f32_e32 v15, v14, v14
	v_fmac_f32_e32 v17, v16, v16
	v_add_f32_e32 v14, v15, v17
	s_waitcnt lgkmcnt(0)
	s_nop 1
	v_mov_b32_e32 v18, v172
	v_mov_b32_e32 v19, v173
	v_mov_b32_e32 v20, v174
	v_mov_b32_e32 v21, v175
	v_pk_add_f32 v[12:13], v[12:13], v[20:21]
	v_pk_add_f32 v[10:11], v[10:11], v[18:19]
	global_store_dwordx4 v[24:25], v[10:13], off offset:64
	v_cvt_pk_bf16_f32 v18, v10, v11
	v_cvt_pk_bf16_f32 v19, v12, v13
	global_store_dwordx2 v[22:23], v[18:19], off offset:32
	v_mul_f32_e32 v11, v11, v11
	v_mul_f32_e32 v13, v13, v13
	v_fmac_f32_e32 v11, v10, v10
	v_fmac_f32_e32 v13, v12, v12
	v_add_f32_e32 v10, v11, v13
	v_add_f32_e32 v10, v14, v10
	s_waitcnt lgkmcnt(0)
	s_nop 1
	v_mov_b32_e32 v18, v186
	v_mov_b32_e32 v19, v187
	v_mov_b32_e32 v20, v188
	v_mov_b32_e32 v21, v189
	v_pk_add_f32 v[8:9], v[8:9], v[20:21]
	v_pk_add_f32 v[6:7], v[6:7], v[18:19]
	global_store_dwordx4 v[24:25], v[6:9], off offset:512
	v_cvt_pk_bf16_f32 v18, v6, v7
	v_cvt_pk_bf16_f32 v19, v8, v9
	global_store_dwordx2 v[22:23], v[18:19], off offset:256
	v_mul_f32_e32 v7, v7, v7
	v_mul_f32_e32 v9, v9, v9
	v_fmac_f32_e32 v7, v6, v6
	v_fmac_f32_e32 v9, v8, v8
	v_add_f32_e32 v6, v7, v9
	v_add_f32_e32 v8, v10, v6
	s_waitcnt lgkmcnt(0)
	s_nop 1
	v_mov_b32_e32 v18, v190
	v_mov_b32_e32 v19, v191
	v_mov_b32_e32 v20, v192
	v_mov_b32_e32 v21, v193
	v_pk_add_f32 v[6:7], v[4:5], v[20:21]
	v_pk_add_f32 v[4:5], v[2:3], v[18:19]
	v_mul_f32_e32 v3, v7, v7
	v_mul_f32_e32 v2, v5, v5
	v_fmac_f32_e32 v2, v4, v4
	v_fmac_f32_e32 v3, v6, v6
	v_add_f32_e32 v2, v2, v3
	v_add_f32_e32 v2, v8, v2
	ds_bpermute_b32 v3, v116, v2
	global_store_dwordx4 v[24:25], v[4:7], off offset:576
	s_waitcnt lgkmcnt(0)
	v_add_f32_e32 v2, v2, v3
	ds_bpermute_b32 v3, v117, v2
	v_cvt_pk_bf16_f32 v4, v4, v5
	v_cvt_pk_bf16_f32 v5, v6, v7
	global_store_dwordx2 v[22:23], v[4:5], off offset:288
	s_and_saveexec_b64 s[12:13], s[38:39]
	s_cbranch_execz .LBB0_109
	s_waitcnt lgkmcnt(0)
	v_add_f32_e32 v2, v2, v3
	s_mov_b32 s14, 0x4b800000
	v_fma_f32 v2, v2, s14, 0.5
	v_trunc_f32_e32 v2, v2
	v_mul_f32_e32 v3, 0x2f800000, v2
	v_floor_f32_e32 v3, v3
	v_fmac_f32_e32 v2, 0xcf800000, v3
	v_cvt_u32_f32_e32 v2, v2
	v_cvt_u32_f32_e32 v3, v3
	global_atomic_add_x2 v[114:115], v[2:3], off offset:1408

; __device__ __forceinline__ unsigned cvt_pk_bf16(float lo, float hi) { unsigned r; asm volatile("v_cvt_pk_bf16_f32 %0, %1, %2" : "=v"(r) : "v"(lo), "v"(hi)); return r; }
; __device__ __forceinline__ float ss_rstd(const u64_t* ss, int row) { return __builtin_amdgcn_rsqf((float)ss[row] * (SS_IFX / (float)2048) + 1e-6f); }
;     __device__ __forceinline__ void operator()(const f32x4 (&acc)[2][2][4][2], const Unit& u, int wr, int wc, int fr, int fq) const {
;     ...
;                 const int row = row0 + ai * HALF + m * 16;
;                 const float sc = ss_rstd(ss, row);
;                 bf16_t* rowp = O + (size_t)row * ldc + col0;
; #pragma unroll
;                 for (int bj = 0; bj < 2; ++bj) { const f32x4 v0 = acc[ai][bj][m][0] * sc, v1 = acc[ai][bj][m][1] * sc;
;                     u32x4 w; w.x = cvt_pk_bf16(v0[0], v0[1]); w.y = cvt_pk_bf16(v0[2], v0[3]); w.z = cvt_pk_bf16(v1[0], v1[1]); w.w = cvt_pk_bf16(v1[2], v1[3]);
;                     *(u32x4*)(rowp + bj * HALF) = w; }
;                 asm volatile("" ::: "memory");
;             }
.LBB0_244:
	v_lshl_add_u32 v140, s12, 8, v148
	v_ashrrev_i32_e32 v141, 31, v140
	v_lshl_add_u64 v[142:143], v[140:141], 3, s[84:85]
	flat_load_dwordx2 v[144:145], v[142:143]
	flat_load_dwordx2 v[162:163], v[142:143] offset:128
	flat_load_dwordx2 v[164:165], v[142:143] offset:256
	flat_load_dwordx2 v[166:167], v[142:143] offset:384
	flat_load_dwordx2 v[168:169], v[142:143] offset:1024
	flat_load_dwordx2 v[170:171], v[142:143] offset:1152
	flat_load_dwordx2 v[172:173], v[142:143] offset:1280
	flat_load_dwordx2 v[174:175], v[142:143] offset:1408
	v_lshl_or_b32 v146, s13, 8, v150
	v_ashrrev_i32_e32 v147, 31, v146
	v_lshlrev_b64 v[146:147], 1, v[146:147]
	s_andn2_b64 vcc, exec, s[38:39]
	s_waitcnt vmcnt(0) lgkmcnt(0)
	v_ffbh_u32_e32 v141, v145
	v_min_u32_e32 v141, 32, v141
	v_lshlrev_b64 v[144:145], v141, v[144:145]
	v_min_u32_e32 v144, 1, v144
	v_or_b32_e32 v144, v145, v144
	v_cvt_f32_u32_e32 v152, v144
	v_sub_u32_e32 v141, 32, v141
	v_mov_b64_e32 v[144:145], s[22:23]
	v_mad_i64_i32 v[154:155], s[12:13], v140, s79, v[144:145]
	v_ldexp_f32 v141, v152, v141
	v_fmamk_f32 v141, v141, 0x2e000000, v207
	v_rsq_f32_e32 v152, v141
	v_lshl_add_u64 v[154:155], v[154:155], 0, v[146:147]
	v_pk_mul_f32 v[128:129], v[128:129], v[152:153] op_sel_hi:[1,0]
	v_pk_mul_f32 v[126:127], v[126:127], v[152:153] op_sel_hi:[1,0]
	v_pk_mul_f32 v[124:125], v[124:125], v[152:153] op_sel_hi:[1,0]
	v_pk_mul_f32 v[122:123], v[122:123], v[152:153] op_sel_hi:[1,0]
	v_pk_mul_f32 v[120:121], v[120:121], v[152:153] op_sel_hi:[1,0]
	v_pk_mul_f32 v[118:119], v[118:119], v[152:153] op_sel_hi:[1,0]
	v_pk_mul_f32 v[156:157], v[116:117], v[152:153] op_sel_hi:[1,0]
	v_pk_mul_f32 v[152:153], v[114:115], v[152:153] op_sel_hi:[1,0]
	v_cvt_pk_bf16_f32 v114, v126, v127
	v_cvt_pk_bf16_f32 v115, v128, v129
	v_cvt_pk_bf16_f32 v116, v122, v123
	v_cvt_pk_bf16_f32 v117, v124, v125
	flat_store_dwordx4 v[154:155], v[114:117]
	s_nop 1
	v_cvt_pk_bf16_f32 v114, v118, v119
	v_cvt_pk_bf16_f32 v115, v120, v121
	v_cvt_pk_bf16_f32 v116, v152, v153
	v_cvt_pk_bf16_f32 v117, v156, v157
	flat_store_dwordx4 v[154:155], v[114:117] offset:256
	s_nop 1
	v_mov_b32_e32 v114, v162
	v_mov_b32_e32 v115, v163
	v_ffbh_u32_e32 v116, v115
	v_min_u32_e32 v116, 32, v116
	v_lshlrev_b64 v[114:115], v116, v[114:115]
	v_min_u32_e32 v114, 1, v114
	v_or_b32_e32 v114, v115, v114
	v_cvt_f32_u32_e32 v114, v114
	v_sub_u32_e32 v116, 32, v116
	v_or_b32_e32 v115, 16, v140
	v_ldexp_f32 v114, v114, v116
	v_fmamk_f32 v114, v114, 0x2e000000, v207
	v_rsq_f32_e32 v114, v114
	v_mad_i64_i32 v[116:117], s[12:13], v115, s79, v[144:145]
	v_lshl_add_u64 v[116:117], v[116:117], 0, v[146:147]
	v_pk_mul_f32 v[112:113], v[112:113], v[114:115] op_sel_hi:[1,0]
	v_pk_mul_f32 v[110:111], v[110:111], v[114:115] op_sel_hi:[1,0]
	v_pk_mul_f32 v[108:109], v[108:109], v[114:115] op_sel_hi:[1,0]
	v_pk_mul_f32 v[106:107], v[106:107], v[114:115] op_sel_hi:[1,0]
	v_pk_mul_f32 v[104:105], v[104:105], v[114:115] op_sel_hi:[1,0]
	v_pk_mul_f32 v[102:103], v[102:103], v[114:115] op_sel_hi:[1,0]
	v_pk_mul_f32 v[118:119], v[100:101], v[114:115] op_sel_hi:[1,0]
	v_pk_mul_f32 v[114:115], v[98:99], v[114:115] op_sel_hi:[1,0]
	v_cvt_pk_bf16_f32 v98, v110, v111
	v_cvt_pk_bf16_f32 v99, v112, v113
	v_cvt_pk_bf16_f32 v100, v106, v107
	v_cvt_pk_bf16_f32 v101, v108, v109
	flat_store_dwordx4 v[116:117], v[98:101]
	s_nop 1
	v_cvt_pk_bf16_f32 v98, v102, v103
	v_cvt_pk_bf16_f32 v99, v104, v105
	v_cvt_pk_bf16_f32 v100, v114, v115
	v_cvt_pk_bf16_f32 v101, v118, v119
	flat_store_dwordx4 v[116:117], v[98:101] offset:256
	s_nop 1
	v_mov_b32_e32 v98, v164
	v_mov_b32_e32 v99, v165
	v_ffbh_u32_e32 v100, v99
	v_min_u32_e32 v100, 32, v100
	v_lshlrev_b64 v[98:99], v100, v[98:99]
	v_min_u32_e32 v98, 1, v98
	v_or_b32_e32 v98, v99, v98
	v_cvt_f32_u32_e32 v98, v98
	v_sub_u32_e32 v100, 32, v100
	v_or_b32_e32 v99, 32, v140
	v_ldexp_f32 v98, v98, v100
	v_fmamk_f32 v98, v98, 0x2e000000, v207
	v_rsq_f32_e32 v98, v98
	v_mad_i64_i32 v[100:101], s[12:13], v99, s79, v[144:145]
	v_lshl_add_u64 v[100:101], v[100:101], 0, v[146:147]
	v_pk_mul_f32 v[96:97], v[96:97], v[98:99] op_sel_hi:[1,0]
	v_pk_mul_f32 v[94:95], v[94:95], v[98:99] op_sel_hi:[1,0]
	v_pk_mul_f32 v[92:93], v[92:93], v[98:99] op_sel_hi:[1,0]
	v_pk_mul_f32 v[90:91], v[90:91], v[98:99] op_sel_hi:[1,0]
	v_pk_mul_f32 v[88:89], v[88:89], v[98:99] op_sel_hi:[1,0]
	v_pk_mul_f32 v[86:87], v[86:87], v[98:99] op_sel_hi:[1,0]
	v_pk_mul_f32 v[102:103], v[84:85], v[98:99] op_sel_hi:[1,0]
	v_pk_mul_f32 v[98:99], v[82:83], v[98:99] op_sel_hi:[1,0]
	v_cvt_pk_bf16_f32 v82, v94, v95
	v_cvt_pk_bf16_f32 v83, v96, v97
	v_cvt_pk_bf16_f32 v84, v90, v91
	v_cvt_pk_bf16_f32 v85, v92, v93
	flat_store_dwordx4 v[100:101], v[82:85]
	s_nop 1
	v_cvt_pk_bf16_f32 v82, v86, v87
	v_cvt_pk_bf16_f32 v83, v88, v89
	v_cvt_pk_bf16_f32 v84, v98, v99
	v_cvt_pk_bf16_f32 v85, v102, v103
	flat_store_dwordx4 v[100:101], v[82:85] offset:256
	s_nop 1
	v_mov_b32_e32 v82, v166
	v_mov_b32_e32 v83, v167
	v_ffbh_u32_e32 v84, v83
	v_min_u32_e32 v84, 32, v84
	v_lshlrev_b64 v[82:83], v84, v[82:83]
	v_min_u32_e32 v82, 1, v82
	v_or_b32_e32 v82, v83, v82
	v_cvt_f32_u32_e32 v82, v82
	v_sub_u32_e32 v84, 32, v84
	v_or_b32_e32 v83, 48, v140
	v_ldexp_f32 v82, v82, v84
	v_fmamk_f32 v82, v82, 0x2e000000, v207
	v_rsq_f32_e32 v82, v82
	v_mad_i64_i32 v[84:85], s[12:13], v83, s79, v[144:145]
	v_lshl_add_u64 v[84:85], v[84:85], 0, v[146:147]
	v_pk_mul_f32 v[80:81], v[80:81], v[82:83] op_sel_hi:[1,0]
	v_pk_mul_f32 v[78:79], v[78:79], v[82:83] op_sel_hi:[1,0]
	v_pk_mul_f32 v[76:77], v[76:77], v[82:83] op_sel_hi:[1,0]
	v_pk_mul_f32 v[74:75], v[74:75], v[82:83] op_sel_hi:[1,0]
	v_pk_mul_f32 v[72:73], v[72:73], v[82:83] op_sel_hi:[1,0]
; __device__ __forceinline__ unsigned cvt_pk_bf16(float lo, float hi) { unsigned r; asm volatile("v_cvt_pk_bf16_f32 %0, %1, %2" : "=v"(r) : "v"(lo), "v"(hi)); return r; }
; __device__ __forceinline__ float ss_rstd(const u64_t* ss, int row) { return __builtin_amdgcn_rsqf((float)ss[row] * (SS_IFX / (float)2048) + 1e-6f); }
;     __device__ __forceinline__ void operator()(const f32x4 (&acc)[2][2][4][2], const Unit& u, int wr, int wc, int fr, int fq) const {
;     ...
;                 const int row = row0 + ai * HALF + m * 16;
;                 const float sc = ss_rstd(ss, row);
;                 bf16_t* rowp = O + (size_t)row * ldc + col0;
; #pragma unroll
;                 for (int bj = 0; bj < 2; ++bj) { const f32x4 v0 = acc[ai][bj][m][0] * sc, v1 = acc[ai][bj][m][1] * sc;
;                     u32x4 w; w.x = cvt_pk_bf16(v0[0], v0[1]); w.y = cvt_pk_bf16(v0[2], v0[3]); w.z = cvt_pk_bf16(v1[0], v1[1]); w.w = cvt_pk_bf16(v1[2], v1[3]);
;                     *(u32x4*)(rowp + bj * HALF) = w; }
;                 asm volatile("" ::: "memory");
;             }
	v_pk_mul_f32 v[70:71], v[70:71], v[82:83] op_sel_hi:[1,0]
	v_pk_mul_f32 v[86:87], v[68:69], v[82:83] op_sel_hi:[1,0]
	v_pk_mul_f32 v[82:83], v[66:67], v[82:83] op_sel_hi:[1,0]
	v_cvt_pk_bf16_f32 v66, v78, v79
	v_cvt_pk_bf16_f32 v67, v80, v81
	v_cvt_pk_bf16_f32 v68, v74, v75
	v_cvt_pk_bf16_f32 v69, v76, v77
	flat_store_dwordx4 v[84:85], v[66:69]
	s_nop 1
	v_cvt_pk_bf16_f32 v66, v70, v71
	v_cvt_pk_bf16_f32 v67, v72, v73
	v_cvt_pk_bf16_f32 v68, v82, v83
	v_cvt_pk_bf16_f32 v69, v86, v87
	flat_store_dwordx4 v[84:85], v[66:69] offset:256
	s_nop 1
	v_mov_b32_e32 v66, v168
	v_mov_b32_e32 v67, v169
	v_ffbh_u32_e32 v68, v67
	v_min_u32_e32 v68, 32, v68
	v_lshlrev_b64 v[66:67], v68, v[66:67]
	v_min_u32_e32 v66, 1, v66
	v_or_b32_e32 v66, v67, v66
	v_cvt_f32_u32_e32 v66, v66
	v_sub_u32_e32 v68, 32, v68
	v_add_u32_e32 v67, 0x80, v140
	v_ldexp_f32 v66, v66, v68
	v_fmamk_f32 v66, v66, 0x2e000000, v207
	v_rsq_f32_e32 v66, v66
	v_mad_i64_i32 v[68:69], s[12:13], v67, s79, v[144:145]
	v_lshl_add_u64 v[68:69], v[68:69], 0, v[146:147]
	v_pk_mul_f32 v[64:65], v[64:65], v[66:67] op_sel_hi:[1,0]
	v_pk_mul_f32 v[62:63], v[62:63], v[66:67] op_sel_hi:[1,0]
	v_pk_mul_f32 v[60:61], v[60:61], v[66:67] op_sel_hi:[1,0]
	v_pk_mul_f32 v[58:59], v[58:59], v[66:67] op_sel_hi:[1,0]
	v_pk_mul_f32 v[56:57], v[56:57], v[66:67] op_sel_hi:[1,0]
	v_pk_mul_f32 v[54:55], v[54:55], v[66:67] op_sel_hi:[1,0]
	v_pk_mul_f32 v[70:71], v[52:53], v[66:67] op_sel_hi:[1,0]
	v_pk_mul_f32 v[66:67], v[50:51], v[66:67] op_sel_hi:[1,0]
	v_cvt_pk_bf16_f32 v50, v62, v63
	v_cvt_pk_bf16_f32 v51, v64, v65
	v_cvt_pk_bf16_f32 v52, v58, v59
	v_cvt_pk_bf16_f32 v53, v60, v61
	flat_store_dwordx4 v[68:69], v[50:53]
	s_nop 1
	v_cvt_pk_bf16_f32 v50, v54, v55
	v_cvt_pk_bf16_f32 v51, v56, v57
	v_cvt_pk_bf16_f32 v52, v66, v67
	v_cvt_pk_bf16_f32 v53, v70, v71
	flat_store_dwordx4 v[68:69], v[50:53] offset:256
	s_nop 1
	v_mov_b32_e32 v50, v170
	v_mov_b32_e32 v51, v171
	v_ffbh_u32_e32 v52, v51
	v_min_u32_e32 v52, 32, v52
	v_lshlrev_b64 v[50:51], v52, v[50:51]
	v_min_u32_e32 v50, 1, v50
	v_or_b32_e32 v50, v51, v50
	v_cvt_f32_u32_e32 v50, v50
	v_sub_u32_e32 v52, 32, v52
	v_add_u32_e32 v51, 0x90, v140
	v_ldexp_f32 v50, v50, v52
	v_fmamk_f32 v50, v50, 0x2e000000, v207
	v_rsq_f32_e32 v50, v50
	v_mad_i64_i32 v[52:53], s[12:13], v51, s79, v[144:145]
	v_lshl_add_u64 v[52:53], v[52:53], 0, v[146:147]
	v_pk_mul_f32 v[48:49], v[48:49], v[50:51] op_sel_hi:[1,0]
	v_pk_mul_f32 v[46:47], v[46:47], v[50:51] op_sel_hi:[1,0]
	v_pk_mul_f32 v[44:45], v[44:45], v[50:51] op_sel_hi:[1,0]
	v_pk_mul_f32 v[42:43], v[42:43], v[50:51] op_sel_hi:[1,0]
	v_pk_mul_f32 v[40:41], v[40:41], v[50:51] op_sel_hi:[1,0]
	v_pk_mul_f32 v[38:39], v[38:39], v[50:51] op_sel_hi:[1,0]
	v_pk_mul_f32 v[54:55], v[36:37], v[50:51] op_sel_hi:[1,0]
	v_pk_mul_f32 v[50:51], v[34:35], v[50:51] op_sel_hi:[1,0]
	v_cvt_pk_bf16_f32 v34, v46, v47
	v_cvt_pk_bf16_f32 v35, v48, v49
	v_cvt_pk_bf16_f32 v36, v42, v43
	v_cvt_pk_bf16_f32 v37, v44, v45
	flat_store_dwordx4 v[52:53], v[34:37]
	s_nop 1
	v_cvt_pk_bf16_f32 v34, v38, v39
	v_cvt_pk_bf16_f32 v35, v40, v41
	v_cvt_pk_bf16_f32 v36, v50, v51
	v_cvt_pk_bf16_f32 v37, v54, v55
	flat_store_dwordx4 v[52:53], v[34:37] offset:256
	s_nop 1
	v_mov_b32_e32 v34, v172
	v_mov_b32_e32 v35, v173
	v_ffbh_u32_e32 v36, v35
	v_min_u32_e32 v36, 32, v36
	v_lshlrev_b64 v[34:35], v36, v[34:35]
	v_min_u32_e32 v34, 1, v34
	v_or_b32_e32 v34, v35, v34
	v_cvt_f32_u32_e32 v34, v34
	v_sub_u32_e32 v36, 32, v36
	v_add_u32_e32 v35, 0xa0, v140
	v_ldexp_f32 v34, v34, v36
	v_fmamk_f32 v34, v34, 0x2e000000, v207
	v_rsq_f32_e32 v34, v34
	v_mad_i64_i32 v[36:37], s[12:13], v35, s79, v[144:145]
	v_lshl_add_u64 v[36:37], v[36:37], 0, v[146:147]
	v_pk_mul_f32 v[32:33], v[32:33], v[34:35] op_sel_hi:[1,0]
	v_pk_mul_f32 v[30:31], v[30:31], v[34:35] op_sel_hi:[1,0]
	v_pk_mul_f32 v[28:29], v[28:29], v[34:35] op_sel_hi:[1,0]
	v_pk_mul_f32 v[26:27], v[26:27], v[34:35] op_sel_hi:[1,0]
	v_pk_mul_f32 v[24:25], v[24:25], v[34:35] op_sel_hi:[1,0]
	v_pk_mul_f32 v[22:23], v[22:23], v[34:35] op_sel_hi:[1,0]
	v_pk_mul_f32 v[38:39], v[20:21], v[34:35] op_sel_hi:[1,0]
	v_pk_mul_f32 v[34:35], v[18:19], v[34:35] op_sel_hi:[1,0]
	v_cvt_pk_bf16_f32 v18, v30, v31
	v_cvt_pk_bf16_f32 v19, v32, v33
	v_cvt_pk_bf16_f32 v20, v26, v27
	v_cvt_pk_bf16_f32 v21, v28, v29
	flat_store_dwordx4 v[36:37], v[18:21]
	s_nop 1
	v_cvt_pk_bf16_f32 v18, v22, v23
	v_cvt_pk_bf16_f32 v19, v24, v25
	v_cvt_pk_bf16_f32 v20, v34, v35
	v_cvt_pk_bf16_f32 v21, v38, v39
	flat_store_dwordx4 v[36:37], v[18:21] offset:256
	s_nop 1
	v_mov_b32_e32 v18, v174
	v_mov_b32_e32 v19, v175
	v_ffbh_u32_e32 v20, v19
	v_min_u32_e32 v20, 32, v20
	v_lshlrev_b64 v[18:19], v20, v[18:19]
	v_min_u32_e32 v18, 1, v18
	v_or_b32_e32 v18, v19, v18
	v_cvt_f32_u32_e32 v18, v18
	v_sub_u32_e32 v20, 32, v20
	v_add_u32_e32 v19, 0xb0, v140
	v_ldexp_f32 v18, v18, v20
	v_fmamk_f32 v18, v18, 0x2e000000, v207
	v_rsq_f32_e32 v18, v18
	v_mad_i64_i32 v[20:21], s[12:13], v19, s79, v[144:145]
	v_lshl_add_u64 v[20:21], v[20:21], 0, v[146:147]
	v_pk_mul_f32 v[16:17], v[16:17], v[18:19] op_sel_hi:[1,0]
	v_pk_mul_f32 v[14:15], v[14:15], v[18:19] op_sel_hi:[1,0]
	v_pk_mul_f32 v[12:13], v[12:13], v[18:19] op_sel_hi:[1,0]
	v_pk_mul_f32 v[10:11], v[10:11], v[18:19] op_sel_hi:[1,0]
	v_pk_mul_f32 v[8:9], v[8:9], v[18:19] op_sel_hi:[1,0]
	v_pk_mul_f32 v[6:7], v[6:7], v[18:19] op_sel_hi:[1,0]
	v_pk_mul_f32 v[22:23], v[4:5], v[18:19] op_sel_hi:[1,0]
	v_pk_mul_f32 v[18:19], v[2:3], v[18:19] op_sel_hi:[1,0]
	v_cvt_pk_bf16_f32 v2, v14, v15
	v_cvt_pk_bf16_f32 v3, v16, v17
	v_cvt_pk_bf16_f32 v4, v10, v11
	v_cvt_pk_bf16_f32 v5, v12, v13
	flat_store_dwordx4 v[20:21], v[2:5]
	s_mov_b64 s[12:13], -1
	s_nop 0
	v_cvt_pk_bf16_f32 v2, v6, v7
	v_cvt_pk_bf16_f32 v3, v8, v9
	v_cvt_pk_bf16_f32 v4, v18, v19
	v_cvt_pk_bf16_f32 v5, v22, v23
	flat_store_dwordx4 v[20:21], v[2:5] offset:256
	s_cbranch_vccnz .LBB0_237
	s_andn2_b64 vcc, exec, s[0:1]
	s_cbranch_vccnz .LBB0_236
	s_barrier
	s_branch .LBB0_236

; __global__ void __launch_bounds__(NTHR, 2) mega_fwd(Args a0) {
	.amdhsa_kernel _Z8mega_fwd4Args
		.amdhsa_group_segment_fixed_size 0
		.amdhsa_private_segment_fixed_size 0
		.amdhsa_kernarg_size 408
		.amdhsa_user_sgpr_count 2
		.amdhsa_user_sgpr_dispatch_ptr 0
		.amdhsa_user_sgpr_queue_ptr 0
		.amdhsa_user_sgpr_kernarg_segment_ptr 1
		.amdhsa_user_sgpr_dispatch_id 0
		.amdhsa_user_sgpr_kernarg_preload_length 0
		.amdhsa_user_sgpr_kernarg_preload_offset 0
		.amdhsa_user_sgpr_private_segment_size 0
		.amdhsa_uses_dynamic_stack 0
		.amdhsa_enable_private_segment 0
		.amdhsa_system_sgpr_workgroup_id_x 1
		.amdhsa_system_sgpr_workgroup_id_y 0
		.amdhsa_system_sgpr_workgroup_id_z 0
		.amdhsa_system_sgpr_workgroup_info 0
		.amdhsa_system_vgpr_workitem_id 2
		.amdhsa_next_free_vgpr 256
		.amdhsa_next_free_sgpr 102
		.amdhsa_accum_offset 256
		.amdhsa_reserve_vcc 1
		.amdhsa_float_round_mode_32 0
		.amdhsa_float_round_mode_16_64 0
		.amdhsa_float_denorm_mode_32 3
		.amdhsa_float_denorm_mode_16_64 3
		.amdhsa_dx10_clamp 1
		.amdhsa_ieee_mode 1
		.amdhsa_fp16_overflow 0
		.amdhsa_tg_split 0
		.amdhsa_exception_fp_ieee_invalid_op 0
		.amdhsa_exception_fp_denorm_src 0
		.amdhsa_exception_fp_ieee_div_zero 0
		.amdhsa_exception_fp_ieee_overflow 0
		.amdhsa_exception_fp_ieee_underflow 0
		.amdhsa_exception_fp_ieee_inexact 0
		.amdhsa_exception_int_div_zero 0
	.end_amdhsa_kernel

; __global__ void __launch_bounds__(NTHR, 2) mega_fwd(Args a0) {
amdhsa.kernels:
  - .agpr_count:     0
    .args:
      - .offset:         0
        .size:           152
        .value_kind:     by_value
      - .offset:         152
        .size:           4
        .value_kind:     hidden_block_count_x
      - .offset:         156
        .size:           4
        .value_kind:     hidden_block_count_y
      - .offset:         160
        .size:           4
        .value_kind:     hidden_block_count_z
      - .offset:         164
        .size:           2
        .value_kind:     hidden_group_size_x
      - .offset:         166
        .size:           2
        .value_kind:     hidden_group_size_y
      - .offset:         168
        .size:           2
        .value_kind:     hidden_group_size_z
      - .offset:         170
        .size:           2
        .value_kind:     hidden_remainder_x
      - .offset:         172
        .size:           2
        .value_kind:     hidden_remainder_y
      - .offset:         174
        .size:           2
        .value_kind:     hidden_remainder_z
      - .offset:         192
        .size:           8
        .value_kind:     hidden_global_offset_x
      - .offset:         200
        .size:           8
        .value_kind:     hidden_global_offset_y
      - .offset:         208
        .size:           8
        .value_kind:     hidden_global_offset_z
      - .offset:         216
        .size:           2
        .value_kind:     hidden_grid_dims
      - .offset:         240
        .size:           8
        .value_kind:     hidden_multigrid_sync_arg
      - .offset:         272
        .size:           4
        .value_kind:     hidden_dynamic_lds_size
    .group_segment_fixed_size: 0
    .kernarg_segment_align: 8
    .kernarg_segment_size: 408
    .language:       OpenCL C
    .language_version:
      - 2
      - 0
    .max_flat_workgroup_size: 512
    .name:           _Z8mega_fwd4Args
    .private_segment_fixed_size: 0
    .sgpr_count:     108
    .sgpr_spill_count: 213
    .symbol:         _Z8mega_fwd4Args.kd
    .uniform_work_group_size: 1
    .uses_dynamic_stack: false
    .vgpr_count:     256
    .vgpr_spill_count: 0
    .wavefront_size: 64
